# phase-1 copier stop threshold 680
# speedup vs baseline: 1.0045x; 1.0045x over previous
.Lcp1_entry:
	v_readfirstlane_b32 s0, v192
	v_lshlrev_b32_e32 v16, 4, v192
	s_add_u32 s4, s38, 0xc7b7100
	s_addc_u32 s5, s39, 0
	s_add_u32 s6, s38, 0xc7b7200
	s_addc_u32 s7, s39, 0
	s_lshr_b32 s0, s0, 6
	s_mov_b32 s1, 0
	s_mov_b32 s30, 2
	v_mov_b32_e32 v93, 0
	v_mov_b32_e32 v94, 1
	v_mov_b32_e32 v95, 16
	v_mov_b32_e32 v96, 20
	v_add_u32_e32 v17, 0x2000, v16
	v_add_u32_e32 v18, 0x4000, v16
	v_add_u32_e32 v19, 0x6000, v16
	v_add_u32_e32 v20, 0x8000, v16
	v_add_u32_e32 v21, 0xa000, v16
	v_add_u32_e32 v22, 0xc000, v16
	v_add_u32_e32 v23, 0xe000, v16
	v_add_u32_e32 v104, 0x10000, v16
	v_add_u32_e32 v105, 0x12000, v16
	v_add_u32_e32 v106, 0x14000, v16
	v_add_u32_e32 v107, 0x16000, v16
	v_add_u32_e32 v108, 0x18000, v16
	v_add_u32_e32 v109, 0x1a000, v16
	v_add_u32_e32 v110, 0x1c000, v16
	v_add_u32_e32 v111, 0x1e000, v16
	s_barrier
	s_cmp_lg_u32 s0, 0
	s_cbranch_scc1 .Lcp1_p0
	s_mov_b64 s[22:23], exec
	s_mov_b64 exec, 1
	global_load_dword v118, v93, s[6:7] sc1
	v_mov_b32_e32 v117, 0xa80
	s_waitcnt vmcnt(0)
	v_readfirstlane_b32 s25, v118
	s_cmpk_gt_u32 s25, 0x2a8
	s_cbranch_scc1 .Lcp1_pnone
	v_mov_b32_e32 v117, 2
	global_atomic_add v117, v93, v117, s[4:5] sc0
	s_waitcnt vmcnt(0)

.Lcp1_ac_A_j:
	s_lshl_b32 s18, s18, 17
	v_add_u32_e32 v92, s24, v16
	s_add_u32 s14, s36, s19
	s_addc_u32 s15, s37, 0
	s_add_u32 s14, s14, s18
	s_addc_u32 s15, s15, 0
	s_add_u32 s12, s12, s18
	s_addc_u32 s13, s13, 0
	s_add_u32 s12, s12, 0x2000
	s_addc_u32 s13, s13, 0
	global_load_dwordx4 v[180:183], v16, s[12:13] nt
	global_load_dwordx4 v[184:187], v17, s[12:13] nt
	global_load_dwordx4 v[188:191], v18, s[12:13] nt
	global_load_dwordx4 v[196:199], v19, s[12:13] nt
	global_load_dwordx4 v[200:203], v20, s[12:13] nt
	global_load_dwordx4 v[204:207], v21, s[12:13] nt
	global_load_dwordx4 v[208:211], v22, s[12:13] nt
	global_load_dwordx4 v[212:215], v23, s[12:13] nt
	global_load_dwordx4 v[216:219], v104, s[12:13] nt
	global_load_dwordx4 v[220:223], v105, s[12:13] nt
	global_load_dwordx4 v[224:227], v106, s[12:13] nt
	global_load_dwordx4 v[228:231], v107, s[12:13] nt
	global_load_dwordx4 v[244:247], v108, s[12:13] nt
	global_load_dwordx4 v[248:251], v109, s[12:13] nt
	global_load_dwordx4 v[4:7], v110, s[12:13] nt
	global_load_dwordx4 v[8:11], v92, s[12:13] nt
	s_waitcnt vmcnt(31)
	global_store_dwordx4 v16, v[30:33], s[10:11] nt
	s_waitcnt vmcnt(31)
	global_store_dwordx4 v17, v[34:37], s[10:11] nt
	s_waitcnt vmcnt(31)
	global_store_dwordx4 v18, v[38:41], s[10:11] nt
	s_waitcnt vmcnt(31)
	global_store_dwordx4 v19, v[42:45], s[10:11] nt
	s_waitcnt vmcnt(31)
	global_store_dwordx4 v20, v[46:49], s[10:11] nt
	s_waitcnt vmcnt(31)
	global_store_dwordx4 v21, v[50:53], s[10:11] nt
	s_waitcnt vmcnt(31)
	global_store_dwordx4 v22, v[54:57], s[10:11] nt
	s_waitcnt vmcnt(31)
	global_store_dwordx4 v23, v[58:61], s[10:11] nt
	s_waitcnt vmcnt(31)
	global_store_dwordx4 v104, v[62:65], s[10:11] nt
	s_waitcnt vmcnt(31)
	global_store_dwordx4 v105, v[66:69], s[10:11] nt
	s_waitcnt vmcnt(31)
	global_store_dwordx4 v106, v[70:73], s[10:11] nt
	s_waitcnt vmcnt(31)
	global_store_dwordx4 v107, v[74:77], s[10:11] nt
	s_waitcnt vmcnt(31)
	global_store_dwordx4 v108, v[164:167], s[10:11] nt
	s_waitcnt vmcnt(31)
	global_store_dwordx4 v109, v[168:171], s[10:11] nt
	s_waitcnt vmcnt(31)
	global_store_dwordx4 v110, v[172:175], s[10:11] nt
	s_waitcnt vmcnt(31)
	global_store_dwordx4 v91, v[176:179], s[10:11] nt
	s_cmp_lg_u32 s0, 0
	s_cbranch_scc1 .Lcp1_A_s4
	s_mov_b64 s[22:23], exec
	s_mov_b64 exec, 1
	s_cmp_lg_u32 s1, 0
	s_cbranch_scc1 .Lcp1_A_s4stop
	s_waitcnt vmcnt(32)
	v_readfirstlane_b32 s25, v118
	s_cmpk_gt_u32 s25, 0x2a8
	s_cselect_b32 s1, 1, 0
	v_readfirstlane_b32 s26, v117
	s_cmpk_ge_u32 s26, 0xa80
	s_cselect_b32 s27, 1, 0
	s_or_b32 s1, s1, s27
	s_branch .Lcp1_A_s4pub

.Lcp1_ac_B_j:
	s_lshl_b32 s18, s18, 17
	v_add_u32_e32 v91, s24, v16
	s_add_u32 s10, s36, s19
	s_addc_u32 s11, s37, 0
	s_add_u32 s10, s10, s18
	s_addc_u32 s11, s11, 0
	s_add_u32 s8, s8, s18
	s_addc_u32 s9, s9, 0
	s_add_u32 s8, s8, 0x2000
	s_addc_u32 s9, s9, 0
	global_load_dwordx4 v[30:33], v16, s[8:9] nt
	global_load_dwordx4 v[34:37], v17, s[8:9] nt
	global_load_dwordx4 v[38:41], v18, s[8:9] nt
	global_load_dwordx4 v[42:45], v19, s[8:9] nt
	global_load_dwordx4 v[46:49], v20, s[8:9] nt
	global_load_dwordx4 v[50:53], v21, s[8:9] nt
	global_load_dwordx4 v[54:57], v22, s[8:9] nt
	global_load_dwordx4 v[58:61], v23, s[8:9] nt
	global_load_dwordx4 v[62:65], v104, s[8:9] nt
	global_load_dwordx4 v[66:69], v105, s[8:9] nt
	global_load_dwordx4 v[70:73], v106, s[8:9] nt
	global_load_dwordx4 v[74:77], v107, s[8:9] nt
	global_load_dwordx4 v[164:167], v108, s[8:9] nt
	global_load_dwordx4 v[168:171], v109, s[8:9] nt
	global_load_dwordx4 v[172:175], v110, s[8:9] nt
	global_load_dwordx4 v[176:179], v91, s[8:9] nt
	s_waitcnt vmcnt(31)
	global_store_dwordx4 v16, v[180:183], s[14:15] nt
	s_waitcnt vmcnt(31)
	global_store_dwordx4 v17, v[184:187], s[14:15] nt
	s_waitcnt vmcnt(31)
	global_store_dwordx4 v18, v[188:191], s[14:15] nt
	s_waitcnt vmcnt(31)
	global_store_dwordx4 v19, v[196:199], s[14:15] nt
	s_waitcnt vmcnt(31)
	global_store_dwordx4 v20, v[200:203], s[14:15] nt
	s_waitcnt vmcnt(31)
	global_store_dwordx4 v21, v[204:207], s[14:15] nt
	s_waitcnt vmcnt(31)
	global_store_dwordx4 v22, v[208:211], s[14:15] nt
	s_waitcnt vmcnt(31)
	global_store_dwordx4 v23, v[212:215], s[14:15] nt
	s_waitcnt vmcnt(31)
	global_store_dwordx4 v104, v[216:219], s[14:15] nt
	s_waitcnt vmcnt(31)
	global_store_dwordx4 v105, v[220:223], s[14:15] nt
	s_waitcnt vmcnt(31)
	global_store_dwordx4 v106, v[224:227], s[14:15] nt
	s_waitcnt vmcnt(31)
	global_store_dwordx4 v107, v[228:231], s[14:15] nt
	s_waitcnt vmcnt(31)
	global_store_dwordx4 v108, v[244:247], s[14:15] nt
	s_waitcnt vmcnt(31)
	global_store_dwordx4 v109, v[248:251], s[14:15] nt
	s_waitcnt vmcnt(31)
	global_store_dwordx4 v110, v[4:7], s[14:15] nt
	s_waitcnt vmcnt(31)
	global_store_dwordx4 v92, v[8:11], s[14:15] nt
	s_cmp_lg_u32 s0, 0
	s_cbranch_scc1 .Lcp1_B_s4
	s_mov_b64 s[22:23], exec
	s_mov_b64 exec, 1
	s_cmp_lg_u32 s1, 0
	s_cbranch_scc1 .Lcp1_B_s4stop
	s_waitcnt vmcnt(32)
	v_readfirstlane_b32 s25, v118
	s_cmpk_gt_u32 s25, 0x2a8
	s_cselect_b32 s1, 1, 0
	v_readfirstlane_b32 s26, v117
	s_cmpk_ge_u32 s26, 0xa80
	s_cselect_b32 s27, 1, 0
	s_or_b32 s1, s1, s27
	s_branch .Lcp1_B_s4pub
